# v33 + every work-group starts the L2 write-back (buffer_wbl2) when it arrives at a grid barrier, before its arrival atomic
# baseline (speedup 1.0000x reference)
; __device__ __forceinline__ unsigned xb_add(unsigned* p, unsigned v) { return __hip_atomic_fetch_add(p, v, __ATOMIC_RELAXED, __HIP_MEMORY_SCOPE_AGENT); }
; __device__ __forceinline__ void xcd_barrier(const XcdBarrier& b) {
;     ...
;         const unsigned old = xb_add(&bar[XB_XSUB(b.x)], 1u);
;         const unsigned gen = old / nloc;
;         if (old + 1u == (gen + 1u) * nloc) {
;             __builtin_amdgcn_fence(__ATOMIC_RELEASE, "agent");
.LBB0_567:
	s_mov_b64 s[8:9], exec
	s_lshl_b32 s0, s0, 8
	v_mbcnt_lo_u32_b32 v1, s8, 0
	s_add_u32 s6, s38, s0
	v_mbcnt_hi_u32_b32 v1, s9, v1
	s_addc_u32 s7, s39, 0
	v_cmp_eq_u32_e32 vcc, 0, v1
	s_and_saveexec_b64 s[12:13], vcc
	s_cbranch_execz .LBB0_569
	s_bcnt1_i32_b64 s0, s[8:9]
	v_mov_b32_e32 v4, s0
	v_mov_b32_e32 v5, 0x1000
	buffer_wbl2 sc1
	global_atomic_add v4, v5, v4, s[6:7] offset:1024 sc0

; __device__ __forceinline__ unsigned xb_add(unsigned* p, unsigned v) { return __hip_atomic_fetch_add(p, v, __ATOMIC_RELAXED, __HIP_MEMORY_SCOPE_AGENT); }
; __device__ __forceinline__ void xcd_barrier(const XcdBarrier& b) {
;     ...
;         const unsigned old = xb_add(&bar[XB_XSUB(b.x)], 1u);
;         const unsigned gen = old / nloc;
;         if (old + 1u == (gen + 1u) * nloc) {
;             __builtin_amdgcn_fence(__ATOMIC_RELEASE, "agent");
.LBB0_628:
	s_mov_b64 s[12:13], exec
	s_lshl_b32 s0, s0, 8
	v_mbcnt_lo_u32_b32 v1, s12, 0
	s_add_u32 s6, s38, s0
	v_mbcnt_hi_u32_b32 v1, s13, v1
	s_addc_u32 s7, s39, 0
	v_cmp_eq_u32_e32 vcc, 0, v1
	s_and_saveexec_b64 s[14:15], vcc
	s_cbranch_execz .LBB0_630
	s_bcnt1_i32_b64 s0, s[12:13]
	v_mov_b32_e32 v4, s0
	v_mov_b32_e32 v5, 0x1000
	buffer_wbl2 sc1
	global_atomic_add v4, v5, v4, s[6:7] offset:1024 sc0

; __device__ __forceinline__ unsigned xb_add(unsigned* p, unsigned v) { return __hip_atomic_fetch_add(p, v, __ATOMIC_RELAXED, __HIP_MEMORY_SCOPE_AGENT); }
; __device__ __forceinline__ void xcd_barrier(const XcdBarrier& b) {
;     ...
;         const unsigned old = xb_add(&bar[XB_XSUB(b.x)], 1u);
;         const unsigned gen = old / nloc;
;         if (old + 1u == (gen + 1u) * nloc) {
;             __builtin_amdgcn_fence(__ATOMIC_RELEASE, "agent");
.LBB0_826:
	s_mov_b64 s[12:13], exec
	s_lshl_b32 s0, s0, 8
	v_mbcnt_lo_u32_b32 v1, s12, 0
	s_add_u32 s8, s38, s0
	v_mbcnt_hi_u32_b32 v1, s13, v1
	s_addc_u32 s9, s39, 0
	v_cmp_eq_u32_e32 vcc, 0, v1
	s_and_saveexec_b64 s[14:15], vcc
	s_cbranch_execz .LBB0_828
	s_bcnt1_i32_b64 s0, s[12:13]
	v_mov_b32_e32 v4, s0
	v_mov_b32_e32 v5, 0x1000
	buffer_wbl2 sc1
	global_atomic_add v4, v5, v4, s[8:9] offset:1024 sc0

; __device__ __forceinline__ unsigned xb_add(unsigned* p, unsigned v) { return __hip_atomic_fetch_add(p, v, __ATOMIC_RELAXED, __HIP_MEMORY_SCOPE_AGENT); }
; __device__ __forceinline__ void xcd_barrier(const XcdBarrier& b) {
;     ...
;         const unsigned old = xb_add(&bar[XB_XSUB(b.x)], 1u);
;         const unsigned gen = old / nloc;
;         if (old + 1u == (gen + 1u) * nloc) {
;             __builtin_amdgcn_fence(__ATOMIC_RELEASE, "agent");
.LBB0_1132:
	s_mov_b64 s[8:9], exec
	s_lshl_b32 s0, s0, 8
	v_mbcnt_lo_u32_b32 v1, s8, 0
	s_add_u32 s6, s38, s0
	v_mbcnt_hi_u32_b32 v1, s9, v1
	s_addc_u32 s7, s39, 0
	v_cmp_eq_u32_e32 vcc, 0, v1
	s_and_saveexec_b64 s[10:11], vcc
	s_cbranch_execz .LBB0_1134
	s_bcnt1_i32_b64 s0, s[8:9]
	v_mov_b32_e32 v4, s0
	v_mov_b32_e32 v5, 0x1000
	buffer_wbl2 sc1
	global_atomic_add v4, v5, v4, s[6:7] offset:1024 sc0

; __device__ __forceinline__ unsigned xb_add(unsigned* p, unsigned v) { return __hip_atomic_fetch_add(p, v, __ATOMIC_RELAXED, __HIP_MEMORY_SCOPE_AGENT); }
; __device__ __forceinline__ void xcd_barrier(const XcdBarrier& b) {
;     ...
;         const unsigned old = xb_add(&bar[XB_XSUB(b.x)], 1u);
;         const unsigned gen = old / nloc;
;         if (old + 1u == (gen + 1u) * nloc) {
;             __builtin_amdgcn_fence(__ATOMIC_RELEASE, "agent");
.LBB0_2076:
	s_mov_b64 s[6:7], exec
	s_lshl_b32 s3, s3, 8
	v_mbcnt_lo_u32_b32 v1, s6, 0
	s_add_u32 s4, s38, s3
	v_mbcnt_hi_u32_b32 v1, s7, v1
	s_addc_u32 s5, s39, 0
	v_cmp_eq_u32_e32 vcc, 0, v1
	s_and_saveexec_b64 s[8:9], vcc
	s_cbranch_execz .LBB0_2078
	s_bcnt1_i32_b64 s3, s[6:7]
	v_mov_b32_e32 v4, s3
	v_mov_b32_e32 v5, 0x1000
	buffer_wbl2 sc1
	global_atomic_add v4, v5, v4, s[4:5] offset:1024 sc0

; __device__ __forceinline__ unsigned xb_add(unsigned* p, unsigned v) { return __hip_atomic_fetch_add(p, v, __ATOMIC_RELAXED, __HIP_MEMORY_SCOPE_AGENT); }
; __device__ __forceinline__ void xcd_barrier(const XcdBarrier& b) {
;     ...
;         const unsigned old = xb_add(&bar[XB_XSUB(b.x)], 1u);
;         const unsigned gen = old / nloc;
;         if (old + 1u == (gen + 1u) * nloc) {
;             __builtin_amdgcn_fence(__ATOMIC_RELEASE, "agent");
.LBB0_2178:
	s_mov_b64 s[8:9], exec
	s_lshl_b32 s3, s3, 8
	v_mbcnt_lo_u32_b32 v1, s8, 0
	s_add_u32 s6, s38, s3
	v_mbcnt_hi_u32_b32 v1, s9, v1
	s_addc_u32 s7, s39, 0
	v_cmp_eq_u32_e32 vcc, 0, v1
	s_and_saveexec_b64 s[10:11], vcc
	s_cbranch_execz .LBB0_2180
	s_bcnt1_i32_b64 s3, s[8:9]
	v_mov_b32_e32 v4, s3
	v_mov_b32_e32 v5, 0x1000
	buffer_wbl2 sc1
	global_atomic_add v4, v5, v4, s[6:7] offset:1024 sc0
